# D4 top-k: first radix digit placed right below the common prefix of the valid keys (finer first histogram, fewer candidates in later passes)
# speedup vs baseline: 1.0067x; 1.0001x over previous
; __device__ __forceinline__ unsigned fkey(float x) {
;     if (x == 0.0f) x = 0.0f;
;     const unsigned u = __float_as_uint(x);
;     return (u & 0x80000000u) ? ~u : (u | 0x80000000u);
; }
; __device__ __forceinline__ void dsa_index_phase(const Params& p, unsigned char* smem) {
;     ...
;             unsigned u[32];
; #pragma unroll
;             for (int i = 0; i < 32; ++i) {
;                 u[i] = 0u;
;                 if (i < ni) { const int s = i * 64 + lane; if (s <= t) u[i] = fkey(srow[s]); }
;             }
.Ltk_ld_end:
	s_waitcnt lgkmcnt(0)
	v_add_f32_e32 v0, 0, v0
	v_cmp_ge_u32_e64 s[2:3], s8, v124
	v_ashrrev_i32_e32 v120, 31, v0
	v_or_b32_e32 v120, 0x80000000, v120
	v_xnor_b32_e32 v0, v120, v0
	v_cndmask_b32_e64 v0, -1, v0, s[2:3]
	v_mov_b32_e32 v123, 0
	v_readfirstlane_b32 s6, v0
	s_nop 1
	v_xor_b32_e32 v120, s6, v0
	v_cndmask_b32_e64 v120, 0, v120, s[2:3]
	v_or_b32_e32 v123, v123, v120
	v_add_f32_e32 v1, 0, v1
	v_cmp_ge_u32_e64 s[4:5], s8, v156
	v_ashrrev_i32_e32 v121, 31, v1
	v_or_b32_e32 v121, 0x80000000, v121
	v_xnor_b32_e32 v1, v121, v1
	v_cndmask_b32_e64 v1, -1, v1, s[4:5]
	v_xor_b32_e32 v121, s6, v1
	v_cndmask_b32_e64 v121, 0, v121, s[4:5]
	v_or_b32_e32 v123, v123, v121
	v_add_f32_e32 v2, 0, v2
	v_cmp_ge_u32_e64 s[2:3], s8, v157
	v_ashrrev_i32_e32 v120, 31, v2
	v_or_b32_e32 v120, 0x80000000, v120
	v_xnor_b32_e32 v2, v120, v2
	v_cndmask_b32_e64 v2, -1, v2, s[2:3]
	v_xor_b32_e32 v120, s6, v2
	v_cndmask_b32_e64 v120, 0, v120, s[2:3]
	v_or_b32_e32 v123, v123, v120
	v_add_f32_e32 v3, 0, v3
	v_cmp_ge_u32_e64 s[4:5], s8, v158
	v_ashrrev_i32_e32 v121, 31, v3
	v_or_b32_e32 v121, 0x80000000, v121
	v_xnor_b32_e32 v3, v121, v3
	v_cndmask_b32_e64 v3, -1, v3, s[4:5]
	v_xor_b32_e32 v121, s6, v3
	v_cndmask_b32_e64 v121, 0, v121, s[4:5]
	v_or_b32_e32 v123, v123, v121
	s_cmp_le_u32 s9, 4
	s_cbranch_scc1 .Ltk_cv_end
	v_add_f32_e32 v4, 0, v4
	v_cmp_ge_u32_e64 s[2:3], s8, v159
	v_ashrrev_i32_e32 v120, 31, v4
	v_or_b32_e32 v120, 0x80000000, v120
	v_xnor_b32_e32 v4, v120, v4
	v_cndmask_b32_e64 v4, -1, v4, s[2:3]
	v_xor_b32_e32 v120, s6, v4
	v_cndmask_b32_e64 v120, 0, v120, s[2:3]
	v_or_b32_e32 v123, v123, v120
	v_add_f32_e32 v5, 0, v5
	v_cmp_ge_u32_e64 s[4:5], s8, v160
	v_ashrrev_i32_e32 v121, 31, v5
	v_or_b32_e32 v121, 0x80000000, v121
	v_xnor_b32_e32 v5, v121, v5
	v_cndmask_b32_e64 v5, -1, v5, s[4:5]
	v_xor_b32_e32 v121, s6, v5
	v_cndmask_b32_e64 v121, 0, v121, s[4:5]
	v_or_b32_e32 v123, v123, v121
	v_add_f32_e32 v6, 0, v6
	v_cmp_ge_u32_e64 s[2:3], s8, v161
	v_ashrrev_i32_e32 v120, 31, v6
	v_or_b32_e32 v120, 0x80000000, v120
	v_xnor_b32_e32 v6, v120, v6
	v_cndmask_b32_e64 v6, -1, v6, s[2:3]
	v_xor_b32_e32 v120, s6, v6
	v_cndmask_b32_e64 v120, 0, v120, s[2:3]
	v_or_b32_e32 v123, v123, v120
	v_add_f32_e32 v7, 0, v7
	v_cmp_ge_u32_e64 s[4:5], s8, v162
	v_ashrrev_i32_e32 v121, 31, v7
	v_or_b32_e32 v121, 0x80000000, v121
	v_xnor_b32_e32 v7, v121, v7
	v_cndmask_b32_e64 v7, -1, v7, s[4:5]
	v_xor_b32_e32 v121, s6, v7
	v_cndmask_b32_e64 v121, 0, v121, s[4:5]
	v_or_b32_e32 v123, v123, v121
	s_cmp_le_u32 s9, 8
	s_cbranch_scc1 .Ltk_cv_end
	v_add_f32_e32 v8, 0, v8
	v_cmp_ge_u32_e64 s[2:3], s8, v163
	v_ashrrev_i32_e32 v120, 31, v8
	v_or_b32_e32 v120, 0x80000000, v120
	v_xnor_b32_e32 v8, v120, v8
	v_cndmask_b32_e64 v8, -1, v8, s[2:3]
	v_xor_b32_e32 v120, s6, v8
	v_cndmask_b32_e64 v120, 0, v120, s[2:3]
	v_or_b32_e32 v123, v123, v120
	v_add_f32_e32 v9, 0, v9
	v_cmp_ge_u32_e64 s[4:5], s8, v164
	v_ashrrev_i32_e32 v121, 31, v9
	v_or_b32_e32 v121, 0x80000000, v121
	v_xnor_b32_e32 v9, v121, v9
	v_cndmask_b32_e64 v9, -1, v9, s[4:5]
	v_xor_b32_e32 v121, s6, v9
	v_cndmask_b32_e64 v121, 0, v121, s[4:5]
	v_or_b32_e32 v123, v123, v121
	v_add_f32_e32 v10, 0, v10
	v_cmp_ge_u32_e64 s[2:3], s8, v165
	v_ashrrev_i32_e32 v120, 31, v10
	v_or_b32_e32 v120, 0x80000000, v120
	v_xnor_b32_e32 v10, v120, v10
	v_cndmask_b32_e64 v10, -1, v10, s[2:3]
	v_xor_b32_e32 v120, s6, v10
	v_cndmask_b32_e64 v120, 0, v120, s[2:3]
	v_or_b32_e32 v123, v123, v120
	v_add_f32_e32 v11, 0, v11
	v_cmp_ge_u32_e64 s[4:5], s8, v166
	v_ashrrev_i32_e32 v121, 31, v11
	v_or_b32_e32 v121, 0x80000000, v121
	v_xnor_b32_e32 v11, v121, v11
	v_cndmask_b32_e64 v11, -1, v11, s[4:5]
	v_xor_b32_e32 v121, s6, v11
	v_cndmask_b32_e64 v121, 0, v121, s[4:5]
	v_or_b32_e32 v123, v123, v121
	s_cmp_le_u32 s9, 12
	s_cbranch_scc1 .Ltk_cv_end
	v_add_f32_e32 v12, 0, v12
	v_cmp_ge_u32_e64 s[2:3], s8, v167
	v_ashrrev_i32_e32 v120, 31, v12
	v_or_b32_e32 v120, 0x80000000, v120
	v_xnor_b32_e32 v12, v120, v12
	v_cndmask_b32_e64 v12, -1, v12, s[2:3]
	v_xor_b32_e32 v120, s6, v12
	v_cndmask_b32_e64 v120, 0, v120, s[2:3]
	v_or_b32_e32 v123, v123, v120
	v_add_f32_e32 v13, 0, v13
	v_cmp_ge_u32_e64 s[4:5], s8, v168
	v_ashrrev_i32_e32 v121, 31, v13
	v_or_b32_e32 v121, 0x80000000, v121
	v_xnor_b32_e32 v13, v121, v13
	v_cndmask_b32_e64 v13, -1, v13, s[4:5]
	v_xor_b32_e32 v121, s6, v13
	v_cndmask_b32_e64 v121, 0, v121, s[4:5]
	v_or_b32_e32 v123, v123, v121
	v_add_f32_e32 v14, 0, v14
	v_cmp_ge_u32_e64 s[2:3], s8, v169
	v_ashrrev_i32_e32 v120, 31, v14
	v_or_b32_e32 v120, 0x80000000, v120
	v_xnor_b32_e32 v14, v120, v14
	v_cndmask_b32_e64 v14, -1, v14, s[2:3]
	v_xor_b32_e32 v120, s6, v14
	v_cndmask_b32_e64 v120, 0, v120, s[2:3]
	v_or_b32_e32 v123, v123, v120
	v_add_f32_e32 v15, 0, v15
	v_cmp_ge_u32_e64 s[4:5], s8, v170
	v_ashrrev_i32_e32 v121, 31, v15
	v_or_b32_e32 v121, 0x80000000, v121
	v_xnor_b32_e32 v15, v121, v15
	v_cndmask_b32_e64 v15, -1, v15, s[4:5]
	v_xor_b32_e32 v121, s6, v15
	v_cndmask_b32_e64 v121, 0, v121, s[4:5]
	v_or_b32_e32 v123, v123, v121
	s_cmp_le_u32 s9, 16
	s_cbranch_scc1 .Ltk_cv_end
; __device__ __forceinline__ unsigned fkey(float x) {
;     if (x == 0.0f) x = 0.0f;
;     const unsigned u = __float_as_uint(x);
;     return (u & 0x80000000u) ? ~u : (u | 0x80000000u);
; }
; __device__ __forceinline__ void dsa_index_phase(const Params& p, unsigned char* smem) {
;     ...
;             unsigned u[32];
; #pragma unroll
;             for (int i = 0; i < 32; ++i) {
;                 u[i] = 0u;
;                 if (i < ni) { const int s = i * 64 + lane; if (s <= t) u[i] = fkey(srow[s]); }
;             }
	v_add_f32_e32 v16, 0, v16
	v_cmp_ge_u32_e64 s[2:3], s8, v171
	v_ashrrev_i32_e32 v120, 31, v16
	v_or_b32_e32 v120, 0x80000000, v120
	v_xnor_b32_e32 v16, v120, v16
	v_cndmask_b32_e64 v16, -1, v16, s[2:3]
	v_xor_b32_e32 v120, s6, v16
	v_cndmask_b32_e64 v120, 0, v120, s[2:3]
	v_or_b32_e32 v123, v123, v120
	v_add_f32_e32 v17, 0, v17
	v_cmp_ge_u32_e64 s[4:5], s8, v172
	v_ashrrev_i32_e32 v121, 31, v17
	v_or_b32_e32 v121, 0x80000000, v121
	v_xnor_b32_e32 v17, v121, v17
	v_cndmask_b32_e64 v17, -1, v17, s[4:5]
	v_xor_b32_e32 v121, s6, v17
	v_cndmask_b32_e64 v121, 0, v121, s[4:5]
	v_or_b32_e32 v123, v123, v121
	v_add_f32_e32 v18, 0, v18
	v_cmp_ge_u32_e64 s[2:3], s8, v173
	v_ashrrev_i32_e32 v120, 31, v18
	v_or_b32_e32 v120, 0x80000000, v120
	v_xnor_b32_e32 v18, v120, v18
	v_cndmask_b32_e64 v18, -1, v18, s[2:3]
	v_xor_b32_e32 v120, s6, v18
	v_cndmask_b32_e64 v120, 0, v120, s[2:3]
	v_or_b32_e32 v123, v123, v120
	v_add_f32_e32 v19, 0, v19
	v_cmp_ge_u32_e64 s[4:5], s8, v174
	v_ashrrev_i32_e32 v121, 31, v19
	v_or_b32_e32 v121, 0x80000000, v121
	v_xnor_b32_e32 v19, v121, v19
	v_cndmask_b32_e64 v19, -1, v19, s[4:5]
	v_xor_b32_e32 v121, s6, v19
	v_cndmask_b32_e64 v121, 0, v121, s[4:5]
	v_or_b32_e32 v123, v123, v121
	s_cmp_le_u32 s9, 20
	s_cbranch_scc1 .Ltk_cv_end
	v_add_f32_e32 v20, 0, v20
	v_cmp_ge_u32_e64 s[2:3], s8, v175
	v_ashrrev_i32_e32 v120, 31, v20
	v_or_b32_e32 v120, 0x80000000, v120
	v_xnor_b32_e32 v20, v120, v20
	v_cndmask_b32_e64 v20, -1, v20, s[2:3]
	v_xor_b32_e32 v120, s6, v20
	v_cndmask_b32_e64 v120, 0, v120, s[2:3]
	v_or_b32_e32 v123, v123, v120
	v_add_f32_e32 v21, 0, v21
	v_cmp_ge_u32_e64 s[4:5], s8, v176
	v_ashrrev_i32_e32 v121, 31, v21
	v_or_b32_e32 v121, 0x80000000, v121
	v_xnor_b32_e32 v21, v121, v21
	v_cndmask_b32_e64 v21, -1, v21, s[4:5]
	v_xor_b32_e32 v121, s6, v21
	v_cndmask_b32_e64 v121, 0, v121, s[4:5]
	v_or_b32_e32 v123, v123, v121
	v_add_f32_e32 v22, 0, v22
	v_cmp_ge_u32_e64 s[2:3], s8, v177
	v_ashrrev_i32_e32 v120, 31, v22
	v_or_b32_e32 v120, 0x80000000, v120
	v_xnor_b32_e32 v22, v120, v22
	v_cndmask_b32_e64 v22, -1, v22, s[2:3]
	v_xor_b32_e32 v120, s6, v22
	v_cndmask_b32_e64 v120, 0, v120, s[2:3]
	v_or_b32_e32 v123, v123, v120
	v_add_f32_e32 v23, 0, v23
	v_cmp_ge_u32_e64 s[4:5], s8, v178
	v_ashrrev_i32_e32 v121, 31, v23
	v_or_b32_e32 v121, 0x80000000, v121
	v_xnor_b32_e32 v23, v121, v23
	v_cndmask_b32_e64 v23, -1, v23, s[4:5]
	v_xor_b32_e32 v121, s6, v23
	v_cndmask_b32_e64 v121, 0, v121, s[4:5]
	v_or_b32_e32 v123, v123, v121
	s_cmp_le_u32 s9, 24
	s_cbranch_scc1 .Ltk_cv_end
	v_add_f32_e32 v24, 0, v24
	v_cmp_ge_u32_e64 s[2:3], s8, v179
	v_ashrrev_i32_e32 v120, 31, v24
	v_or_b32_e32 v120, 0x80000000, v120
	v_xnor_b32_e32 v24, v120, v24
	v_cndmask_b32_e64 v24, -1, v24, s[2:3]
	v_xor_b32_e32 v120, s6, v24
	v_cndmask_b32_e64 v120, 0, v120, s[2:3]
	v_or_b32_e32 v123, v123, v120
	v_add_f32_e32 v25, 0, v25
	v_cmp_ge_u32_e64 s[4:5], s8, v180
	v_ashrrev_i32_e32 v121, 31, v25
	v_or_b32_e32 v121, 0x80000000, v121
	v_xnor_b32_e32 v25, v121, v25
	v_cndmask_b32_e64 v25, -1, v25, s[4:5]
	v_xor_b32_e32 v121, s6, v25
	v_cndmask_b32_e64 v121, 0, v121, s[4:5]
	v_or_b32_e32 v123, v123, v121
	v_add_f32_e32 v26, 0, v26
	v_cmp_ge_u32_e64 s[2:3], s8, v181
	v_ashrrev_i32_e32 v120, 31, v26
	v_or_b32_e32 v120, 0x80000000, v120
	v_xnor_b32_e32 v26, v120, v26
	v_cndmask_b32_e64 v26, -1, v26, s[2:3]
	v_xor_b32_e32 v120, s6, v26
	v_cndmask_b32_e64 v120, 0, v120, s[2:3]
	v_or_b32_e32 v123, v123, v120
	v_add_f32_e32 v27, 0, v27
	v_cmp_ge_u32_e64 s[4:5], s8, v182
	v_ashrrev_i32_e32 v121, 31, v27
	v_or_b32_e32 v121, 0x80000000, v121
	v_xnor_b32_e32 v27, v121, v27
	v_cndmask_b32_e64 v27, -1, v27, s[4:5]
	v_xor_b32_e32 v121, s6, v27
	v_cndmask_b32_e64 v121, 0, v121, s[4:5]
	v_or_b32_e32 v123, v123, v121
	s_cmp_le_u32 s9, 28
	s_cbranch_scc1 .Ltk_cv_end
	v_add_f32_e32 v28, 0, v28
	v_cmp_ge_u32_e64 s[2:3], s8, v183
	v_ashrrev_i32_e32 v120, 31, v28
	v_or_b32_e32 v120, 0x80000000, v120
	v_xnor_b32_e32 v28, v120, v28
	v_cndmask_b32_e64 v28, -1, v28, s[2:3]
	v_xor_b32_e32 v120, s6, v28
	v_cndmask_b32_e64 v120, 0, v120, s[2:3]
	v_or_b32_e32 v123, v123, v120
	v_add_f32_e32 v29, 0, v29
	v_cmp_ge_u32_e64 s[4:5], s8, v184
	v_ashrrev_i32_e32 v121, 31, v29
	v_or_b32_e32 v121, 0x80000000, v121
	v_xnor_b32_e32 v29, v121, v29
	v_cndmask_b32_e64 v29, -1, v29, s[4:5]
	v_xor_b32_e32 v121, s6, v29
	v_cndmask_b32_e64 v121, 0, v121, s[4:5]
	v_or_b32_e32 v123, v123, v121
	v_add_f32_e32 v30, 0, v30
	v_cmp_ge_u32_e64 s[2:3], s8, v185
	v_ashrrev_i32_e32 v120, 31, v30
	v_or_b32_e32 v120, 0x80000000, v120
	v_xnor_b32_e32 v30, v120, v30
	v_cndmask_b32_e64 v30, -1, v30, s[2:3]
	v_xor_b32_e32 v120, s6, v30
	v_cndmask_b32_e64 v120, 0, v120, s[2:3]
	v_or_b32_e32 v123, v123, v120
	v_add_f32_e32 v31, 0, v31
	v_cmp_ge_u32_e64 s[4:5], s8, v186
	v_ashrrev_i32_e32 v121, 31, v31
	v_or_b32_e32 v121, 0x80000000, v121
	v_xnor_b32_e32 v31, v121, v31
	v_cndmask_b32_e64 v31, -1, v31, s[4:5]
	v_xor_b32_e32 v121, s6, v31
	v_cndmask_b32_e64 v121, 0, v121, s[4:5]
	v_or_b32_e32 v123, v123, v121
; __device__ __forceinline__ void dsa_index_phase(const Params& p, unsigned char* smem) {
;     ...
; #pragma unroll 1
;                 for (int pass = 0; pass < 4; ++pass) {
;                     const int shift = 24 - 8 * pass;
;                     const unsigned hmask = pass == 0 ? 0u : (0xFFFFFFFFu << (shift + 8));
;                     *(u32x4*)(H + lane * 4) = (u32x4){0u, 0u, 0u, 0u};
;                     asm volatile("s_waitcnt lgkmcnt(0)" ::: "memory");
; #pragma unroll
;                     for (int i = 0; i < 32; ++i) if (i < ni) { const unsigned uu = u[i]; if (uu != 0u && (uu & hmask) == prefix) atomicAdd(H + ((uu >> shift) & 255u), 1u); }
.Ltk_cv_end:
	s_nop 1
	v_or_b32_dpp v123, v123, v123 row_shr:1 row_mask:0xf bank_mask:0xf bound_ctrl:1
	s_nop 1
	v_or_b32_dpp v123, v123, v123 row_shr:2 row_mask:0xf bank_mask:0xf bound_ctrl:1
	s_nop 1
	v_or_b32_dpp v123, v123, v123 row_shr:4 row_mask:0xf bank_mask:0xf bound_ctrl:1
	s_nop 1
	v_or_b32_dpp v123, v123, v123 row_shr:8 row_mask:0xf bank_mask:0xf bound_ctrl:1
	s_nop 1
	v_or_b32_dpp v123, v123, v123 row_bcast:15 row_mask:0xa bank_mask:0xf
	s_nop 1
	v_or_b32_dpp v123, v123, v123 row_bcast:31 row_mask:0xc bank_mask:0xf
	s_nop 1
	v_readlane_b32 s3, v123, 63
	s_movk_i32 s82, 0x100
	s_cmp_eq_u32 s3, 0
	s_cbranch_scc0 .Ltk_pfx
	s_mov_b32 s33, s6
	s_branch .Ltk_compact
.Ltk_pfx:
	s_flbit_i32_b32 s7, s3
	s_sub_i32 s11, 24, s7
	s_max_i32 s11, s11, 0
	s_sub_i32 s7, 24, s11
	s_lshr_b32 s10, -1, s7
	s_andn2_b32 s33, s6, s10
	ds_write_b128 v190, v[242:245]
	v_bfe_u32 v120, v0, s11, 8
	v_lshl_add_u32 v120, v120, 2, v155
	ds_add_u32 v120, v227
	v_bfe_u32 v121, v1, s11, 8
	v_lshl_add_u32 v121, v121, 2, v155
	ds_add_u32 v121, v227
	v_bfe_u32 v120, v2, s11, 8
	v_lshl_add_u32 v120, v120, 2, v155
	ds_add_u32 v120, v227
	v_bfe_u32 v121, v3, s11, 8
	v_lshl_add_u32 v121, v121, 2, v155
	ds_add_u32 v121, v227
	s_cmp_le_u32 s9, 4
	s_cbranch_scc1 .Ltk_scan
	v_bfe_u32 v120, v4, s11, 8
	v_lshl_add_u32 v120, v120, 2, v155
	ds_add_u32 v120, v227
	v_bfe_u32 v121, v5, s11, 8
	v_lshl_add_u32 v121, v121, 2, v155
	ds_add_u32 v121, v227
	v_bfe_u32 v120, v6, s11, 8
	v_lshl_add_u32 v120, v120, 2, v155
	ds_add_u32 v120, v227
	v_bfe_u32 v121, v7, s11, 8
	v_lshl_add_u32 v121, v121, 2, v155
	ds_add_u32 v121, v227
	s_cmp_le_u32 s9, 8
	s_cbranch_scc1 .Ltk_scan
	v_bfe_u32 v120, v8, s11, 8
	v_lshl_add_u32 v120, v120, 2, v155
	ds_add_u32 v120, v227
	v_bfe_u32 v121, v9, s11, 8
	v_lshl_add_u32 v121, v121, 2, v155
	ds_add_u32 v121, v227
	v_bfe_u32 v120, v10, s11, 8
	v_lshl_add_u32 v120, v120, 2, v155
	ds_add_u32 v120, v227
	v_bfe_u32 v121, v11, s11, 8
	v_lshl_add_u32 v121, v121, 2, v155
	ds_add_u32 v121, v227
	s_cmp_le_u32 s9, 12
	s_cbranch_scc1 .Ltk_scan
	v_bfe_u32 v120, v12, s11, 8
	v_lshl_add_u32 v120, v120, 2, v155
	ds_add_u32 v120, v227
	v_bfe_u32 v121, v13, s11, 8
	v_lshl_add_u32 v121, v121, 2, v155
	ds_add_u32 v121, v227
	v_bfe_u32 v120, v14, s11, 8
	v_lshl_add_u32 v120, v120, 2, v155
	ds_add_u32 v120, v227
	v_bfe_u32 v121, v15, s11, 8
	v_lshl_add_u32 v121, v121, 2, v155
	ds_add_u32 v121, v227
	s_cmp_le_u32 s9, 16
	s_cbranch_scc1 .Ltk_scan
	v_bfe_u32 v120, v16, s11, 8
	v_lshl_add_u32 v120, v120, 2, v155
	ds_add_u32 v120, v227
	v_bfe_u32 v121, v17, s11, 8
	v_lshl_add_u32 v121, v121, 2, v155
	ds_add_u32 v121, v227
	v_bfe_u32 v120, v18, s11, 8
	v_lshl_add_u32 v120, v120, 2, v155
	ds_add_u32 v120, v227
	v_bfe_u32 v121, v19, s11, 8
	v_lshl_add_u32 v121, v121, 2, v155
	ds_add_u32 v121, v227
	s_cmp_le_u32 s9, 20
	s_cbranch_scc1 .Ltk_scan
	v_bfe_u32 v120, v20, s11, 8
	v_lshl_add_u32 v120, v120, 2, v155
	ds_add_u32 v120, v227
	v_bfe_u32 v121, v21, s11, 8
	v_lshl_add_u32 v121, v121, 2, v155
	ds_add_u32 v121, v227
	v_bfe_u32 v120, v22, s11, 8
	v_lshl_add_u32 v120, v120, 2, v155
	ds_add_u32 v120, v227
	v_bfe_u32 v121, v23, s11, 8
	v_lshl_add_u32 v121, v121, 2, v155
	ds_add_u32 v121, v227
	s_cmp_le_u32 s9, 24
	s_cbranch_scc1 .Ltk_scan
	v_bfe_u32 v120, v24, s11, 8
	v_lshl_add_u32 v120, v120, 2, v155
	ds_add_u32 v120, v227
	v_bfe_u32 v121, v25, s11, 8
	v_lshl_add_u32 v121, v121, 2, v155
	ds_add_u32 v121, v227
	v_bfe_u32 v120, v26, s11, 8
	v_lshl_add_u32 v120, v120, 2, v155
	ds_add_u32 v120, v227
	v_bfe_u32 v121, v27, s11, 8
	v_lshl_add_u32 v121, v121, 2, v155
	ds_add_u32 v121, v227
	s_cmp_le_u32 s9, 28
	s_cbranch_scc1 .Ltk_scan
	v_bfe_u32 v120, v28, s11, 8
	v_lshl_add_u32 v120, v120, 2, v155
	ds_add_u32 v120, v227
	v_bfe_u32 v121, v29, s11, 8
	v_lshl_add_u32 v121, v121, 2, v155
	ds_add_u32 v121, v227
	v_bfe_u32 v120, v30, s11, 8
	v_lshl_add_u32 v120, v120, 2, v155
	ds_add_u32 v120, v227
	v_bfe_u32 v121, v31, s11, 8
	v_lshl_add_u32 v121, v121, 2, v155
	ds_add_u32 v121, v227
	s_branch .Ltk_scan
.Ltk_pass:
	ds_write_b128 v190, v[242:245]
	v_xor_b32_e32 v120, s33, v0
	v_cmp_gt_u32_e32 vcc, s10, v120
	s_cbranch_vccz .Ltk_m0
	v_bfe_u32 v121, v0, s11, 8
	v_lshl_add_u32 v121, v121, 2, v155
	s_and_saveexec_b64 s[2:3], vcc
	ds_add_u32 v121, v227
	s_or_b64 exec, exec, s[2:3]

; __device__ __forceinline__ void dsa_index_phase(const Params& p, unsigned char* smem) {
;     ...
;                     const u32x4 hv = *(const u32x4*)(H + lane * 4);
;                     const int tot = (int)(hv.x + hv.y + hv.z + hv.w);
;                     int rs = tot;
;                     rs += __builtin_amdgcn_update_dpp(0, rs, 0xB1, 0xF, 0xF, true);
;                     rs += __builtin_amdgcn_update_dpp(0, rs, 0x4E, 0xF, 0xF, true);
;                     rs += __builtin_amdgcn_update_dpp(0, rs, 0x141, 0xF, 0xF, true);
;                     rs += __builtin_amdgcn_update_dpp(0, rs, 0x140, 0xF, 0xF, true);
;                     int rowsel = 3, above = 0;
;                     {
;                         const int r3 = __builtin_amdgcn_readlane(rs, 48), r2 = __builtin_amdgcn_readlane(rs, 32), r1 = __builtin_amdgcn_readlane(rs, 16);
;                         if (need > r3) { above = r3; rowsel = 2; if (need > above + r2) { above += r2; rowsel = 1; if (need > above + r1) { above += r1; rowsel = 0; } } }
;                     }
;                     int lsel = rowsel * 16;
;                     for (int k = 15; k >= 0; --k) {
;                         const int cl = __builtin_amdgcn_readlane(tot, rowsel * 16 + k);
;                         if (need <= above + cl) { lsel = rowsel * 16 + k; break; }
;                         above += cl;
;                     }
;                     const int b3 = __builtin_amdgcn_readlane((int)hv.w, lsel), b2 = __builtin_amdgcn_readlane((int)hv.z, lsel), b1 = __builtin_amdgcn_readlane((int)hv.y, lsel);
;                     int bsel = 3;
;                     if (need > above + b3) { above += b3; bsel = 2; if (need > above + b2) { above += b2; bsel = 1; if (need > above + b1) { above += b1; bsel = 0; } } }
;                     prefix |= (unsigned)(lsel * 4 + bsel) << shift;
;                     need -= above;
.Ltk_m31:
.Ltk_scan:
	ds_read_b128 v[132:135], v190
	s_waitcnt lgkmcnt(0)
	v_add_u32_e32 v136, v132, v133
	v_add_u32_e32 v137, v134, v135
	v_add_u32_e32 v136, v136, v137
	v_mov_b32_e32 v137, v136
	s_nop 1
	v_add_u32_dpp v137, v137, v137 row_shr:1 row_mask:0xf bank_mask:0xf bound_ctrl:1
	s_nop 1
	v_add_u32_dpp v137, v137, v137 row_shr:2 row_mask:0xf bank_mask:0xf bound_ctrl:1
	s_nop 1
	v_add_u32_dpp v137, v137, v137 row_shr:4 row_mask:0xf bank_mask:0xf bound_ctrl:1
	s_nop 1
	v_add_u32_dpp v137, v137, v137 row_shr:8 row_mask:0xf bank_mask:0xf bound_ctrl:1
	s_nop 1
	v_add_u32_dpp v137, v137, v137 row_bcast:15 row_mask:0xa bank_mask:0xf
	s_nop 1
	v_add_u32_dpp v137, v137, v137 row_bcast:31 row_mask:0xc bank_mask:0xf
	s_nop 1
	v_cmp_le_u32_e64 s[2:3], s82, v137
	s_ff1_i32_b64 s16, s[2:3]
	v_readlane_b32 s17, v137, s16
	v_readlane_b32 s6, v136, s16
	v_readlane_b32 s0, v132, s16
	v_readlane_b32 s1, v133, s16
	v_readlane_b32 s2, v134, s16
	s_sub_u32 s17, s17, s6
	s_add_u32 s10, s17, s6
	s_add_u32 s0, s17, s0
	s_add_u32 s1, s0, s1
	s_add_u32 s2, s1, s2
	s_mov_b32 s3, 0
	s_cmp_gt_u32 s82, s0
	s_cselect_b32 s17, s0, s17
	s_addc_u32 s3, s3, 0
	s_cmp_gt_u32 s82, s1
	s_cselect_b32 s17, s1, s17
	s_addc_u32 s3, s3, 0
	s_cmp_gt_u32 s82, s2
	s_cselect_b32 s17, s2, s17
	s_addc_u32 s3, s3, 0
	s_cmp_le_u32 s82, s2
	s_cselect_b32 s10, s2, s10
	s_cmp_le_u32 s82, s1
	s_cselect_b32 s10, s1, s10
	s_cmp_le_u32 s82, s0
	s_cselect_b32 s10, s0, s10
	s_lshl_b32 s16, s16, 2
	s_add_u32 s16, s16, s3
	s_lshl_b32 s16, s16, s11
	s_or_b32 s33, s33, s16
	s_cmp_eq_u32 s82, s10
	s_cbranch_scc1 .Ltk_early
	s_sub_u32 s82, s82, s17
	s_cmp_eq_u32 s11, 0
	s_cbranch_scc1 .Ltk_compact
	s_lshl_b32 s10, 1, s11
	s_sub_i32 s11, s11, 8
	s_max_i32 s11, s11, 0
	s_branch .Ltk_pass
